# FFN-in epilogue: the eight row-sum loads of a tile issued together (no load-wait-store ladder)
# speedup vs baseline: 1.0021x; 1.0021x over previous
.LBB0_681:
	v_lshl_add_u32 v164, s6, 8, v155
	s_lshr_b32 s1, s6, 5
	v_ashrrev_i32_e32 v165, 31, v164
	s_mul_i32 s28, s1, 0x1600
	v_lshl_add_u64 v[166:167], v[164:165], 2, s[10:11]
	s_ashr_i32 s29, s28, 31
	global_load_dword v165, v[166:167], off
	global_load_dword v241, v[166:167], off offset:64
	global_load_dword v242, v[166:167], off offset:128
	global_load_dword v243, v[166:167], off offset:192
	global_load_dword v244, v[166:167], off offset:512
	global_load_dword v245, v[166:167], off offset:576
	global_load_dword v246, v[166:167], off offset:640
	global_load_dword v247, v[166:167], off offset:704
	s_lshl_b64 s[28:29], s[28:29], 2
	s_add_u32 s1, s48, s28
	s_addc_u32 s21, s49, s29
	s_lshl_b32 s28, s0, 8
	s_ashr_i32 s29, s28, 31
	s_lshl_b64 s[28:29], s[28:29], 2
	s_add_u32 s1, s1, s28
	s_addc_u32 s6, s21, s29
	s_lshl_b32 s21, s50, 2
	s_add_u32 s28, s1, s21
	s_addc_u32 s29, s6, 0
	v_lshlrev_b32_e32 v96, 2, v154
	global_load_dwordx4 v[108:111], v96, s[28:29]
	global_load_dwordx4 v[104:107], v96, s[28:29] offset:512
	global_load_dwordx4 v[100:103], v96, s[28:29] offset:16
	s_nop 0
	global_load_dwordx4 v[96:99], v96, s[28:29] offset:528
	v_mov_b64_e32 v[168:169], s[12:13]
	s_lshl_b32 s0, s0, 7
	v_mad_i64_i32 v[176:177], s[28:29], v164, s57, v[168:169]
	s_ashr_i32 s1, s0, 31
	s_lshl_b64 s[28:29], s[0:1], 1
	s_lshl_b32 s6, s50, 1
	v_lshl_add_u64 v[176:177], v[176:177], 0, s[28:29]
	v_lshlrev_b32_e32 v152, 1, v154
	v_or_b32_e32 v178, 16, v164
	v_lshl_add_u64 v[176:177], v[176:177], 0, s[6:7]
	v_ashrrev_i32_e32 v179, 31, v178
	v_lshl_add_u64 v[176:177], v[176:177], 0, v[152:153]
	v_lshl_add_u64 v[180:181], v[178:179], 2, s[10:11]
	s_waitcnt vmcnt(0)
	v_fmamk_f32 v165, v165, 0x3a800000, v174
	v_mul_f32_e32 v175, 0x4b800000, v165
	v_cmp_gt_f32_e32 vcc, s58, v165
	s_nop 1
	v_cndmask_b32_e32 v165, v165, v175, vcc
	v_rsq_f32_e32 v165, v165
	s_nop 0
	v_mul_f32_e32 v175, 0x45800000, v165
	v_cndmask_b32_e32 v182, v165, v175, vcc
	v_pk_fma_f32 v[140:141], v[140:141], v[182:183], v[108:109] op_sel_hi:[1,0,1]
	v_pk_fma_f32 v[142:143], v[142:143], v[182:183], v[110:111] op_sel_hi:[1,0,1]
	v_pk_fma_f32 v[134:135], v[134:135], v[182:183], v[106:107] op_sel_hi:[1,0,1]
	v_pk_fma_f32 v[132:133], v[132:133], v[182:183], v[104:105] op_sel_hi:[1,0,1]
	v_pk_fma_f32 v[136:137], v[136:137], v[182:183], v[100:101] op_sel_hi:[1,0,1]
	v_pk_fma_f32 v[138:139], v[138:139], v[182:183], v[102:103] op_sel_hi:[1,0,1]
	v_pk_fma_f32 v[130:131], v[130:131], v[182:183], v[98:99] op_sel_hi:[1,0,1]
	v_pk_fma_f32 v[128:129], v[128:129], v[182:183], v[96:97] op_sel_hi:[1,0,1]
	v_pk_mul_f32 v[182:183], v[142:143], s[18:19] op_sel_hi:[1,0]
	v_pk_mul_f32 v[184:185], v[140:141], s[18:19] op_sel_hi:[1,0]
	v_pk_mul_f32 v[132:133], v[140:141], v[132:133]
	v_pk_mul_f32 v[134:135], v[142:143], v[134:135]
	v_pk_mul_f32 v[140:141], v[138:139], s[18:19] op_sel_hi:[1,0]
	v_pk_mul_f32 v[142:143], v[136:137], s[18:19] op_sel_hi:[1,0]
	v_pk_mul_f32 v[128:129], v[136:137], v[128:129]
	v_pk_mul_f32 v[130:131], v[138:139], v[130:131]
	v_exp_f32_e32 v136, v184
	v_exp_f32_e32 v137, v185
	v_exp_f32_e32 v138, v182
	v_exp_f32_e32 v139, v183
	v_exp_f32_e32 v142, v142
	v_exp_f32_e32 v140, v140
	v_exp_f32_e32 v141, v141
	v_exp_f32_e32 v143, v143
	v_pk_add_f32 v[138:139], v[138:139], 1.0 op_sel_hi:[1,0]
	v_pk_add_f32 v[136:137], v[136:137], 1.0 op_sel_hi:[1,0]
	v_pk_add_f32 v[140:141], v[140:141], 1.0 op_sel_hi:[1,0]
	v_pk_add_f32 v[142:143], v[142:143], 1.0 op_sel_hi:[1,0]
	v_rcp_f32_e32 v136, v136
	v_rcp_f32_e32 v137, v137
	v_rcp_f32_e32 v138, v138
	v_rcp_f32_e32 v139, v139
	v_rcp_f32_e32 v142, v142
	v_rcp_f32_e32 v140, v140
	v_rcp_f32_e32 v141, v141
	v_rcp_f32_e32 v143, v143
	v_pk_mul_f32 v[134:135], v[134:135], v[138:139]
	v_pk_mul_f32 v[132:133], v[132:133], v[136:137]
	v_pk_mul_f32 v[136:137], v[130:131], v[140:141]
	v_pk_mul_f32 v[130:131], v[128:129], v[142:143]
	v_cvt_pk_bf16_f32 v128, v132, v133
	v_cvt_pk_bf16_f32 v129, v134, v135
	v_cvt_pk_bf16_f32 v130, v130, v131
	v_cvt_pk_bf16_f32 v131, v136, v137
	global_store_dwordx4 v[176:177], v[128:131], off
	s_nop 0
	s_nop 0
	v_or_b32_e32 v128, 32, v164
	v_ashrrev_i32_e32 v129, 31, v128
	v_lshl_add_u64 v[132:133], v[128:129], 2, s[10:11]
	v_mad_i64_i32 v[130:131], s[0:1], v178, s57, v[168:169]
	v_lshl_add_u64 v[130:131], v[130:131], 0, s[28:29]
	v_lshl_add_u64 v[130:131], v[130:131], 0, s[6:7]
	v_lshl_add_u64 v[130:131], v[130:131], 0, v[152:153]
	v_fmamk_f32 v129, v241, 0x3a800000, v174
	v_mul_f32_e32 v134, 0x4b800000, v129
	v_cmp_gt_f32_e32 vcc, s58, v129
	s_nop 1
	v_cndmask_b32_e32 v129, v129, v134, vcc
	v_rsq_f32_e32 v129, v129
	s_nop 0
	v_mul_f32_e32 v134, 0x45800000, v129
	v_cndmask_b32_e32 v134, v129, v134, vcc
	v_pk_fma_f32 v[124:125], v[124:125], v[134:135], v[108:109] op_sel_hi:[1,0,1]
	v_pk_fma_f32 v[126:127], v[126:127], v[134:135], v[110:111] op_sel_hi:[1,0,1]
	v_pk_fma_f32 v[118:119], v[118:119], v[134:135], v[106:107] op_sel_hi:[1,0,1]
	v_pk_fma_f32 v[116:117], v[116:117], v[134:135], v[104:105] op_sel_hi:[1,0,1]
	v_pk_fma_f32 v[120:121], v[120:121], v[134:135], v[100:101] op_sel_hi:[1,0,1]
	v_pk_fma_f32 v[122:123], v[122:123], v[134:135], v[102:103] op_sel_hi:[1,0,1]
	v_pk_fma_f32 v[114:115], v[114:115], v[134:135], v[98:99] op_sel_hi:[1,0,1]
	v_pk_fma_f32 v[112:113], v[112:113], v[134:135], v[96:97] op_sel_hi:[1,0,1]
	v_pk_mul_f32 v[134:135], v[126:127], s[18:19] op_sel_hi:[1,0]
	v_pk_mul_f32 v[136:137], v[124:125], s[18:19] op_sel_hi:[1,0]
	v_pk_mul_f32 v[116:117], v[124:125], v[116:117]
	v_pk_mul_f32 v[118:119], v[126:127], v[118:119]
	v_pk_mul_f32 v[124:125], v[122:123], s[18:19] op_sel_hi:[1,0]
	v_pk_mul_f32 v[126:127], v[120:121], s[18:19] op_sel_hi:[1,0]
	v_pk_mul_f32 v[112:113], v[120:121], v[112:113]
	v_pk_mul_f32 v[114:115], v[122:123], v[114:115]
	v_exp_f32_e32 v120, v136
	v_exp_f32_e32 v121, v137
	v_exp_f32_e32 v122, v134
	v_exp_f32_e32 v123, v135
	v_exp_f32_e32 v126, v126
	v_exp_f32_e32 v124, v124
	v_exp_f32_e32 v125, v125
	v_exp_f32_e32 v127, v127
	v_pk_add_f32 v[122:123], v[122:123], 1.0 op_sel_hi:[1,0]
	v_pk_add_f32 v[120:121], v[120:121], 1.0 op_sel_hi:[1,0]
	v_pk_add_f32 v[124:125], v[124:125], 1.0 op_sel_hi:[1,0]
	v_pk_add_f32 v[126:127], v[126:127], 1.0 op_sel_hi:[1,0]
	v_rcp_f32_e32 v120, v120
	v_rcp_f32_e32 v121, v121
	v_rcp_f32_e32 v122, v122
	v_rcp_f32_e32 v123, v123
	v_rcp_f32_e32 v126, v126
	v_rcp_f32_e32 v124, v124
	v_rcp_f32_e32 v125, v125
	v_rcp_f32_e32 v127, v127
	v_pk_mul_f32 v[118:119], v[118:119], v[122:123]
	v_pk_mul_f32 v[116:117], v[116:117], v[120:121]
	v_pk_mul_f32 v[120:121], v[114:115], v[124:125]
	v_pk_mul_f32 v[114:115], v[112:113], v[126:127]
	v_cvt_pk_bf16_f32 v112, v116, v117
	v_cvt_pk_bf16_f32 v113, v118, v119
	v_cvt_pk_bf16_f32 v114, v114, v115
	v_cvt_pk_bf16_f32 v115, v120, v121
	global_store_dwordx4 v[130:131], v[112:115], off
	s_nop 0
	s_nop 0
	v_or_b32_e32 v112, 48, v164
	v_ashrrev_i32_e32 v113, 31, v112
	v_lshl_add_u64 v[116:117], v[112:113], 2, s[10:11]
	v_mad_i64_i32 v[114:115], s[0:1], v128, s57, v[168:169]
	v_lshl_add_u64 v[114:115], v[114:115], 0, s[28:29]
	v_lshl_add_u64 v[114:115], v[114:115], 0, s[6:7]
	v_lshl_add_u64 v[114:115], v[114:115], 0, v[152:153]
	v_fmamk_f32 v113, v242, 0x3a800000, v174
	v_mul_f32_e32 v118, 0x4b800000, v113
	v_cmp_gt_f32_e32 vcc, s58, v113
	s_nop 1
	v_cndmask_b32_e32 v113, v113, v118, vcc
	v_rsq_f32_e32 v113, v113
	s_nop 0
	v_mul_f32_e32 v118, 0x45800000, v113
	v_cndmask_b32_e32 v118, v113, v118, vcc
	v_pk_fma_f32 v[92:93], v[92:93], v[118:119], v[108:109] op_sel_hi:[1,0,1]
	v_pk_fma_f32 v[94:95], v[94:95], v[118:119], v[110:111] op_sel_hi:[1,0,1]
	v_pk_fma_f32 v[86:87], v[86:87], v[118:119], v[106:107] op_sel_hi:[1,0,1]
	v_pk_fma_f32 v[84:85], v[84:85], v[118:119], v[104:105] op_sel_hi:[1,0,1]
	v_pk_fma_f32 v[88:89], v[88:89], v[118:119], v[100:101] op_sel_hi:[1,0,1]
	v_pk_fma_f32 v[90:91], v[90:91], v[118:119], v[102:103] op_sel_hi:[1,0,1]
	v_pk_fma_f32 v[82:83], v[82:83], v[118:119], v[98:99] op_sel_hi:[1,0,1]
	v_pk_fma_f32 v[80:81], v[80:81], v[118:119], v[96:97] op_sel_hi:[1,0,1]
	v_pk_mul_f32 v[118:119], v[94:95], s[18:19] op_sel_hi:[1,0]
	v_pk_mul_f32 v[120:121], v[92:93], s[18:19] op_sel_hi:[1,0]
	v_pk_mul_f32 v[84:85], v[92:93], v[84:85]
	v_pk_mul_f32 v[86:87], v[94:95], v[86:87]
	v_pk_mul_f32 v[92:93], v[90:91], s[18:19] op_sel_hi:[1,0]
	v_pk_mul_f32 v[94:95], v[88:89], s[18:19] op_sel_hi:[1,0]
	v_pk_mul_f32 v[80:81], v[88:89], v[80:81]
	v_pk_mul_f32 v[82:83], v[90:91], v[82:83]
	v_exp_f32_e32 v88, v120
	v_exp_f32_e32 v89, v121
	v_exp_f32_e32 v90, v118
	v_exp_f32_e32 v91, v119
	v_exp_f32_e32 v94, v94
	v_exp_f32_e32 v92, v92
	v_exp_f32_e32 v93, v93
	v_exp_f32_e32 v95, v95
	v_pk_add_f32 v[90:91], v[90:91], 1.0 op_sel_hi:[1,0]
	v_pk_add_f32 v[88:89], v[88:89], 1.0 op_sel_hi:[1,0]
	v_pk_add_f32 v[92:93], v[92:93], 1.0 op_sel_hi:[1,0]
	v_pk_add_f32 v[94:95], v[94:95], 1.0 op_sel_hi:[1,0]
	v_rcp_f32_e32 v88, v88
	v_rcp_f32_e32 v89, v89
	v_rcp_f32_e32 v90, v90
	v_rcp_f32_e32 v91, v91
	v_rcp_f32_e32 v94, v94
	v_rcp_f32_e32 v92, v92
	v_rcp_f32_e32 v93, v93
	v_rcp_f32_e32 v95, v95
	v_pk_mul_f32 v[86:87], v[86:87], v[90:91]
	v_pk_mul_f32 v[84:85], v[84:85], v[88:89]
	v_pk_mul_f32 v[88:89], v[82:83], v[92:93]
	v_pk_mul_f32 v[82:83], v[80:81], v[94:95]
	v_cvt_pk_bf16_f32 v80, v84, v85
	v_cvt_pk_bf16_f32 v81, v86, v87
	v_cvt_pk_bf16_f32 v82, v82, v83
	v_cvt_pk_bf16_f32 v83, v88, v89
	global_store_dwordx4 v[114:115], v[80:83], off
	s_nop 0
	s_nop 0
	v_mad_i64_i32 v[80:81], s[0:1], v112, s57, v[168:169]
	v_lshl_add_u64 v[80:81], v[80:81], 0, s[28:29]
	v_lshl_add_u64 v[80:81], v[80:81], 0, s[6:7]
	v_lshl_add_u64 v[80:81], v[80:81], 0, v[152:153]
	v_fmamk_f32 v82, v243, 0x3a800000, v174
	v_mul_f32_e32 v83, 0x4b800000, v82
	v_cmp_gt_f32_e32 vcc, s58, v82
	s_nop 1
	v_cndmask_b32_e32 v82, v82, v83, vcc
	v_rsq_f32_e32 v82, v82
	s_nop 0
	v_mul_f32_e32 v83, 0x45800000, v82
	v_cndmask_b32_e32 v82, v82, v83, vcc
	v_pk_fma_f32 v[76:77], v[76:77], v[82:83], v[108:109] op_sel_hi:[1,0,1]
	v_pk_fma_f32 v[78:79], v[78:79], v[82:83], v[110:111] op_sel_hi:[1,0,1]
	v_pk_fma_f32 v[70:71], v[70:71], v[82:83], v[106:107] op_sel_hi:[1,0,1]
	v_pk_fma_f32 v[68:69], v[68:69], v[82:83], v[104:105] op_sel_hi:[1,0,1]
	v_pk_fma_f32 v[72:73], v[72:73], v[82:83], v[100:101] op_sel_hi:[1,0,1]
	v_pk_fma_f32 v[74:75], v[74:75], v[82:83], v[102:103] op_sel_hi:[1,0,1]
	v_pk_fma_f32 v[66:67], v[66:67], v[82:83], v[98:99] op_sel_hi:[1,0,1]
	v_pk_fma_f32 v[64:65], v[64:65], v[82:83], v[96:97] op_sel_hi:[1,0,1]
	v_pk_mul_f32 v[82:83], v[78:79], s[18:19] op_sel_hi:[1,0]
	v_pk_mul_f32 v[84:85], v[76:77], s[18:19] op_sel_hi:[1,0]
	v_pk_mul_f32 v[68:69], v[76:77], v[68:69]
	v_pk_mul_f32 v[70:71], v[78:79], v[70:71]
	v_pk_mul_f32 v[76:77], v[74:75], s[18:19] op_sel_hi:[1,0]
	v_pk_mul_f32 v[78:79], v[72:73], s[18:19] op_sel_hi:[1,0]
	v_pk_mul_f32 v[64:65], v[72:73], v[64:65]
	v_pk_mul_f32 v[66:67], v[74:75], v[66:67]
	v_exp_f32_e32 v72, v84
	v_exp_f32_e32 v73, v85
	v_exp_f32_e32 v74, v82
	v_exp_f32_e32 v75, v83
	v_exp_f32_e32 v78, v78
	v_exp_f32_e32 v76, v76
	v_exp_f32_e32 v77, v77
	v_exp_f32_e32 v79, v79
	v_pk_add_f32 v[74:75], v[74:75], 1.0 op_sel_hi:[1,0]
	v_pk_add_f32 v[72:73], v[72:73], 1.0 op_sel_hi:[1,0]
	v_pk_add_f32 v[76:77], v[76:77], 1.0 op_sel_hi:[1,0]
	v_pk_add_f32 v[78:79], v[78:79], 1.0 op_sel_hi:[1,0]
	v_rcp_f32_e32 v72, v72
	v_rcp_f32_e32 v73, v73
	v_rcp_f32_e32 v74, v74
	v_rcp_f32_e32 v75, v75
	v_rcp_f32_e32 v78, v78
	v_rcp_f32_e32 v76, v76
	v_rcp_f32_e32 v77, v77
	v_rcp_f32_e32 v79, v79
	v_pk_mul_f32 v[70:71], v[70:71], v[74:75]
	v_pk_mul_f32 v[68:69], v[68:69], v[72:73]
	v_pk_mul_f32 v[72:73], v[66:67], v[76:77]
	v_pk_mul_f32 v[66:67], v[64:65], v[78:79]
	v_cvt_pk_bf16_f32 v64, v68, v69
	v_cvt_pk_bf16_f32 v65, v70, v71
	v_cvt_pk_bf16_f32 v66, v66, v67
	v_cvt_pk_bf16_f32 v67, v72, v73
	global_store_dwordx4 v[80:81], v[64:67], off
	s_nop 0
	s_nop 0
	v_add_u32_e32 v64, 0x80, v164
	v_mad_i64_i32 v[64:65], s[0:1], v64, s57, v[168:169]
	v_lshl_add_u64 v[64:65], v[64:65], 0, s[28:29]
	v_lshl_add_u64 v[64:65], v[64:65], 0, s[6:7]
	v_lshl_add_u64 v[64:65], v[64:65], 0, v[152:153]
	v_fmamk_f32 v66, v244, 0x3a800000, v174
	v_mul_f32_e32 v67, 0x4b800000, v66
	v_cmp_gt_f32_e32 vcc, s58, v66
	s_nop 1
	v_cndmask_b32_e32 v66, v66, v67, vcc
	v_rsq_f32_e32 v66, v66
	s_nop 0
	v_mul_f32_e32 v67, 0x45800000, v66
	v_cndmask_b32_e32 v66, v66, v67, vcc
	v_pk_fma_f32 v[60:61], v[60:61], v[66:67], v[108:109] op_sel_hi:[1,0,1]
	v_pk_fma_f32 v[62:63], v[62:63], v[66:67], v[110:111] op_sel_hi:[1,0,1]
	v_pk_fma_f32 v[54:55], v[54:55], v[66:67], v[106:107] op_sel_hi:[1,0,1]
	v_pk_fma_f32 v[52:53], v[52:53], v[66:67], v[104:105] op_sel_hi:[1,0,1]
	v_pk_fma_f32 v[56:57], v[56:57], v[66:67], v[100:101] op_sel_hi:[1,0,1]
	v_pk_fma_f32 v[58:59], v[58:59], v[66:67], v[102:103] op_sel_hi:[1,0,1]
	v_pk_fma_f32 v[50:51], v[50:51], v[66:67], v[98:99] op_sel_hi:[1,0,1]
	v_pk_fma_f32 v[48:49], v[48:49], v[66:67], v[96:97] op_sel_hi:[1,0,1]
	v_pk_mul_f32 v[66:67], v[62:63], s[18:19] op_sel_hi:[1,0]
	v_pk_mul_f32 v[68:69], v[60:61], s[18:19] op_sel_hi:[1,0]
	v_pk_mul_f32 v[52:53], v[60:61], v[52:53]
	v_pk_mul_f32 v[54:55], v[62:63], v[54:55]
	v_pk_mul_f32 v[60:61], v[58:59], s[18:19] op_sel_hi:[1,0]
	v_pk_mul_f32 v[62:63], v[56:57], s[18:19] op_sel_hi:[1,0]
	v_pk_mul_f32 v[48:49], v[56:57], v[48:49]
	v_pk_mul_f32 v[50:51], v[58:59], v[50:51]
	v_exp_f32_e32 v56, v68
	v_exp_f32_e32 v57, v69
	v_exp_f32_e32 v58, v66
	v_exp_f32_e32 v59, v67
	v_exp_f32_e32 v62, v62
	v_exp_f32_e32 v60, v60
	v_exp_f32_e32 v61, v61
	v_exp_f32_e32 v63, v63
	v_pk_add_f32 v[58:59], v[58:59], 1.0 op_sel_hi:[1,0]
	v_pk_add_f32 v[56:57], v[56:57], 1.0 op_sel_hi:[1,0]
	v_pk_add_f32 v[60:61], v[60:61], 1.0 op_sel_hi:[1,0]
	v_pk_add_f32 v[62:63], v[62:63], 1.0 op_sel_hi:[1,0]
	v_rcp_f32_e32 v56, v56
	v_rcp_f32_e32 v57, v57
	v_rcp_f32_e32 v58, v58
	v_rcp_f32_e32 v59, v59
	v_rcp_f32_e32 v62, v62
	v_rcp_f32_e32 v60, v60
	v_rcp_f32_e32 v61, v61
	v_rcp_f32_e32 v63, v63
	v_pk_mul_f32 v[54:55], v[54:55], v[58:59]
	v_pk_mul_f32 v[52:53], v[52:53], v[56:57]
	v_pk_mul_f32 v[56:57], v[50:51], v[60:61]
	v_pk_mul_f32 v[50:51], v[48:49], v[62:63]
	v_cvt_pk_bf16_f32 v48, v52, v53
	v_cvt_pk_bf16_f32 v49, v54, v55
	v_cvt_pk_bf16_f32 v50, v50, v51
	v_cvt_pk_bf16_f32 v51, v56, v57
	global_store_dwordx4 v[64:65], v[48:51], off
	s_nop 0
	s_nop 0
	v_add_u32_e32 v48, 0x90, v164
	v_mad_i64_i32 v[48:49], s[0:1], v48, s57, v[168:169]
	v_lshl_add_u64 v[48:49], v[48:49], 0, s[28:29]
	v_lshl_add_u64 v[48:49], v[48:49], 0, s[6:7]
	v_lshl_add_u64 v[48:49], v[48:49], 0, v[152:153]
	v_fmamk_f32 v50, v245, 0x3a800000, v174
	v_mul_f32_e32 v51, 0x4b800000, v50
	v_cmp_gt_f32_e32 vcc, s58, v50
	s_nop 1
	v_cndmask_b32_e32 v50, v50, v51, vcc
	v_rsq_f32_e32 v50, v50
	s_nop 0
	v_mul_f32_e32 v51, 0x45800000, v50
	v_cndmask_b32_e32 v50, v50, v51, vcc
	v_pk_fma_f32 v[44:45], v[44:45], v[50:51], v[108:109] op_sel_hi:[1,0,1]
	v_pk_fma_f32 v[46:47], v[46:47], v[50:51], v[110:111] op_sel_hi:[1,0,1]
	v_pk_fma_f32 v[38:39], v[38:39], v[50:51], v[106:107] op_sel_hi:[1,0,1]
	v_pk_fma_f32 v[36:37], v[36:37], v[50:51], v[104:105] op_sel_hi:[1,0,1]
	v_pk_fma_f32 v[40:41], v[40:41], v[50:51], v[100:101] op_sel_hi:[1,0,1]
	v_pk_fma_f32 v[42:43], v[42:43], v[50:51], v[102:103] op_sel_hi:[1,0,1]
	v_pk_fma_f32 v[34:35], v[34:35], v[50:51], v[98:99] op_sel_hi:[1,0,1]
	v_pk_fma_f32 v[32:33], v[32:33], v[50:51], v[96:97] op_sel_hi:[1,0,1]
	v_pk_mul_f32 v[50:51], v[46:47], s[18:19] op_sel_hi:[1,0]
	v_pk_mul_f32 v[52:53], v[44:45], s[18:19] op_sel_hi:[1,0]
	v_pk_mul_f32 v[36:37], v[44:45], v[36:37]
	v_pk_mul_f32 v[38:39], v[46:47], v[38:39]
	v_pk_mul_f32 v[44:45], v[42:43], s[18:19] op_sel_hi:[1,0]
	v_pk_mul_f32 v[46:47], v[40:41], s[18:19] op_sel_hi:[1,0]
	v_pk_mul_f32 v[32:33], v[40:41], v[32:33]
	v_pk_mul_f32 v[34:35], v[42:43], v[34:35]
	v_exp_f32_e32 v40, v52
	v_exp_f32_e32 v41, v53
	v_exp_f32_e32 v42, v50
	v_exp_f32_e32 v43, v51
	v_exp_f32_e32 v46, v46
	v_exp_f32_e32 v44, v44
	v_exp_f32_e32 v45, v45
	v_exp_f32_e32 v47, v47
	v_pk_add_f32 v[42:43], v[42:43], 1.0 op_sel_hi:[1,0]
	v_pk_add_f32 v[40:41], v[40:41], 1.0 op_sel_hi:[1,0]
	v_pk_add_f32 v[44:45], v[44:45], 1.0 op_sel_hi:[1,0]
	v_pk_add_f32 v[46:47], v[46:47], 1.0 op_sel_hi:[1,0]
	v_rcp_f32_e32 v40, v40
	v_rcp_f32_e32 v41, v41
	v_rcp_f32_e32 v42, v42
	v_rcp_f32_e32 v43, v43
	v_rcp_f32_e32 v46, v46
	v_rcp_f32_e32 v44, v44
	v_rcp_f32_e32 v45, v45
	v_rcp_f32_e32 v47, v47
	v_pk_mul_f32 v[38:39], v[38:39], v[42:43]
	v_pk_mul_f32 v[36:37], v[36:37], v[40:41]
	v_pk_mul_f32 v[40:41], v[34:35], v[44:45]
	v_pk_mul_f32 v[34:35], v[32:33], v[46:47]
	v_cvt_pk_bf16_f32 v32, v36, v37
	v_cvt_pk_bf16_f32 v33, v38, v39
	v_cvt_pk_bf16_f32 v34, v34, v35
	v_cvt_pk_bf16_f32 v35, v40, v41
	global_store_dwordx4 v[48:49], v[32:35], off
	s_nop 0
	s_nop 0
	v_add_u32_e32 v32, 0xa0, v164
	v_mad_i64_i32 v[32:33], s[0:1], v32, s57, v[168:169]
	v_lshl_add_u64 v[32:33], v[32:33], 0, s[28:29]
	v_lshl_add_u64 v[32:33], v[32:33], 0, s[6:7]
	v_lshl_add_u64 v[32:33], v[32:33], 0, v[152:153]
	v_fmamk_f32 v34, v246, 0x3a800000, v174
	v_mul_f32_e32 v35, 0x4b800000, v34
	v_cmp_gt_f32_e32 vcc, s58, v34
	s_nop 1
	v_cndmask_b32_e32 v34, v34, v35, vcc
	v_rsq_f32_e32 v34, v34
	s_nop 0
	v_mul_f32_e32 v35, 0x45800000, v34
	v_cndmask_b32_e32 v34, v34, v35, vcc
	v_pk_fma_f32 v[28:29], v[28:29], v[34:35], v[108:109] op_sel_hi:[1,0,1]
	v_pk_fma_f32 v[30:31], v[30:31], v[34:35], v[110:111] op_sel_hi:[1,0,1]
	v_pk_fma_f32 v[22:23], v[22:23], v[34:35], v[106:107] op_sel_hi:[1,0,1]
	v_pk_fma_f32 v[20:21], v[20:21], v[34:35], v[104:105] op_sel_hi:[1,0,1]
	v_pk_fma_f32 v[24:25], v[24:25], v[34:35], v[100:101] op_sel_hi:[1,0,1]
	v_pk_fma_f32 v[26:27], v[26:27], v[34:35], v[102:103] op_sel_hi:[1,0,1]
	v_pk_fma_f32 v[18:19], v[18:19], v[34:35], v[98:99] op_sel_hi:[1,0,1]
	v_pk_fma_f32 v[16:17], v[16:17], v[34:35], v[96:97] op_sel_hi:[1,0,1]
	v_pk_mul_f32 v[34:35], v[30:31], s[18:19] op_sel_hi:[1,0]
	v_pk_mul_f32 v[36:37], v[28:29], s[18:19] op_sel_hi:[1,0]
	v_pk_mul_f32 v[20:21], v[28:29], v[20:21]
	v_pk_mul_f32 v[22:23], v[30:31], v[22:23]
	v_pk_mul_f32 v[28:29], v[26:27], s[18:19] op_sel_hi:[1,0]
	v_pk_mul_f32 v[30:31], v[24:25], s[18:19] op_sel_hi:[1,0]
	v_pk_mul_f32 v[16:17], v[24:25], v[16:17]
	v_pk_mul_f32 v[18:19], v[26:27], v[18:19]
	v_exp_f32_e32 v24, v36
	v_exp_f32_e32 v25, v37
	v_exp_f32_e32 v26, v34
	v_exp_f32_e32 v27, v35
	v_exp_f32_e32 v30, v30
	v_exp_f32_e32 v28, v28
	v_exp_f32_e32 v29, v29
	v_exp_f32_e32 v31, v31
	v_pk_add_f32 v[26:27], v[26:27], 1.0 op_sel_hi:[1,0]
	v_pk_add_f32 v[24:25], v[24:25], 1.0 op_sel_hi:[1,0]
	v_pk_add_f32 v[28:29], v[28:29], 1.0 op_sel_hi:[1,0]
	v_pk_add_f32 v[30:31], v[30:31], 1.0 op_sel_hi:[1,0]
	v_rcp_f32_e32 v24, v24
	v_rcp_f32_e32 v25, v25
	v_rcp_f32_e32 v26, v26
	v_rcp_f32_e32 v27, v27
	v_rcp_f32_e32 v30, v30
	v_rcp_f32_e32 v28, v28
	v_rcp_f32_e32 v29, v29
	v_rcp_f32_e32 v31, v31
	v_pk_mul_f32 v[22:23], v[22:23], v[26:27]
	v_pk_mul_f32 v[20:21], v[20:21], v[24:25]
	v_pk_mul_f32 v[24:25], v[18:19], v[28:29]
	v_pk_mul_f32 v[18:19], v[16:17], v[30:31]
	v_cvt_pk_bf16_f32 v16, v20, v21
	v_cvt_pk_bf16_f32 v17, v22, v23
	v_cvt_pk_bf16_f32 v18, v18, v19
	v_cvt_pk_bf16_f32 v19, v24, v25
	global_store_dwordx4 v[32:33], v[16:19], off
	s_nop 0
	s_andn2_b64 vcc, exec, s[2:3]
	v_add_u32_e32 v16, 0xb0, v164
	v_mad_i64_i32 v[16:17], s[0:1], v16, s57, v[168:169]
	v_lshl_add_u64 v[16:17], v[16:17], 0, s[28:29]
	v_lshl_add_u64 v[16:17], v[16:17], 0, s[6:7]
	v_lshl_add_u64 v[16:17], v[16:17], 0, v[152:153]
	v_fmamk_f32 v18, v247, 0x3a800000, v174
	v_mul_f32_e32 v19, 0x4b800000, v18
	v_cmp_gt_f32_e64 s[2:3], s58, v18
	s_nop 1
	v_cndmask_b32_e64 v18, v18, v19, s[2:3]
	v_rsq_f32_e32 v18, v18
	s_nop 0
	v_mul_f32_e32 v19, 0x45800000, v18
	v_cndmask_b32_e64 v18, v18, v19, s[2:3]
	v_pk_fma_f32 v[12:13], v[12:13], v[18:19], v[108:109] op_sel_hi:[1,0,1]
	v_pk_fma_f32 v[14:15], v[14:15], v[18:19], v[110:111] op_sel_hi:[1,0,1]
	v_pk_fma_f32 v[6:7], v[6:7], v[18:19], v[106:107] op_sel_hi:[1,0,1]
	v_pk_fma_f32 v[4:5], v[4:5], v[18:19], v[104:105] op_sel_hi:[1,0,1]
	v_pk_fma_f32 v[8:9], v[8:9], v[18:19], v[100:101] op_sel_hi:[1,0,1]
	v_pk_fma_f32 v[10:11], v[10:11], v[18:19], v[102:103] op_sel_hi:[1,0,1]
	v_pk_fma_f32 v[2:3], v[2:3], v[18:19], v[98:99] op_sel_hi:[1,0,1]
	v_pk_fma_f32 v[0:1], v[0:1], v[18:19], v[96:97] op_sel_hi:[1,0,1]
	v_pk_mul_f32 v[18:19], v[14:15], s[18:19] op_sel_hi:[1,0]
	v_pk_mul_f32 v[20:21], v[12:13], s[18:19] op_sel_hi:[1,0]
	v_pk_mul_f32 v[4:5], v[12:13], v[4:5]
	v_pk_mul_f32 v[6:7], v[14:15], v[6:7]
	v_pk_mul_f32 v[12:13], v[10:11], s[18:19] op_sel_hi:[1,0]
	v_pk_mul_f32 v[14:15], v[8:9], s[18:19] op_sel_hi:[1,0]
	v_pk_mul_f32 v[0:1], v[8:9], v[0:1]
	v_pk_mul_f32 v[2:3], v[10:11], v[2:3]
	v_exp_f32_e32 v8, v20
	v_exp_f32_e32 v9, v21
	v_exp_f32_e32 v10, v18
	v_exp_f32_e32 v11, v19
	v_exp_f32_e32 v14, v14
	v_exp_f32_e32 v12, v12
	v_exp_f32_e32 v13, v13
	v_exp_f32_e32 v15, v15
	v_pk_add_f32 v[10:11], v[10:11], 1.0 op_sel_hi:[1,0]
	v_pk_add_f32 v[8:9], v[8:9], 1.0 op_sel_hi:[1,0]
	v_pk_add_f32 v[12:13], v[12:13], 1.0 op_sel_hi:[1,0]
	v_pk_add_f32 v[14:15], v[14:15], 1.0 op_sel_hi:[1,0]
	v_rcp_f32_e32 v8, v8
	v_rcp_f32_e32 v9, v9
	v_rcp_f32_e32 v10, v10
	v_rcp_f32_e32 v11, v11
	v_rcp_f32_e32 v14, v14
	v_rcp_f32_e32 v12, v12
	v_rcp_f32_e32 v13, v13
	v_rcp_f32_e32 v15, v15
	v_pk_mul_f32 v[6:7], v[6:7], v[10:11]
	v_pk_mul_f32 v[4:5], v[4:5], v[8:9]
	v_pk_mul_f32 v[8:9], v[2:3], v[12:13]
	v_pk_mul_f32 v[2:3], v[0:1], v[14:15]
	v_cvt_pk_bf16_f32 v0, v4, v5
	v_cvt_pk_bf16_f32 v1, v6, v7
	v_cvt_pk_bf16_f32 v2, v2, v3
	v_cvt_pk_bf16_f32 v3, v8, v9
	s_mov_b64 s[2:3], -1
	global_store_dwordx4 v[16:17], v[0:3], off
	s_cbranch_vccnz .LBB0_674
	s_andn2_b64 vcc, exec, s[8:9]
	s_cbranch_vccnz .LBB0_673
	s_barrier
	s_branch .LBB0_673
